# final candidate variant: phase-B items-first fraction mode 100 (100 = 1/4, 101 = 3/4 of WGs)
# baseline (speedup 1.0000x reference)
; __global__ void __launch_bounds__(256, 2) hybrid_megakernel(Params p) {
;     ...
;     xcd_barrier(xg);
;     for (int vb = bid; vb < 512; vb += nb) {
;       { const int q2 = vb >> 3; inproj_tile<4>(p, l, (vb & 7) * 16 + (q2 & 15), 8 + (q2 >> 4), lds); }
;       if (vb < 64) cmp_item(p, l, vb, lds);
;       else {
;         const int j = vb - 64;
;         if (vb >= 256) { const int i2 = (vb - 256) >> 3; inproj_tile<2>(p, l, (vb & 7) * 16 + (i2 & 15), 24 + (i2 >> 4), lds); }
;         win_item(p, j, lds);
;         if (j + 448 < 512) win_item(p, j + 448, lds);
;         for (int it = j; it < 1536; it += 448) dil_item(p, it, lds);
;       }
;     }
.LBB0_213:
	s_or_b64 exec, exec, s[0:1]
	v_readlane_b32 s0, v235, 23
	v_readlane_b32 s1, v235, 24
	s_andn2_b64 vcc, exec, s[0:1]
	s_waitcnt lgkmcnt(0)
	v_cndmask_b32_e64 v0, 0, 1, s[0:1]
	v_cmp_ne_u32_e64 s[2:3], 1, v0
	s_barrier
	s_nop 0
	v_writelane_b32 v234, s2, 27
	s_nop 1
	v_writelane_b32 v234, s3, 28
	s_cbranch_vccnz .LBB0_298
	v_readlane_b32 s0, v234, 24
	s_mul_i32 s28, s0, 0xd00
	s_lshl_b32 s29, s0, 1
	v_readlane_b32 s30, v234, 18
	v_readlane_b32 s31, v234, 17
	v_readlane_b32 s34, v234, 14
	v_readlane_b32 s35, v234, 13
	v_readlane_b32 s36, v235, 0
	s_nop 1
	s_bfe_u32 s98, s36, 0x20003
	s_cmp_eq_u32 s98, 0
	s_cselect_b32 s98, 1, 0
	s_branch .LBB0_217
